# accumulator zeroing per GEMM tile with v_pk_mov_b32 pairs (63 instead of 126 moves) in 8 of the GEMM loops, on top of v12
# speedup vs baseline: 1.0040x; 1.0040x over previous
; template <class Epi>
; __device__ __forceinline__ void gemm_phase(LAS unsigned char* lds, const Gemm g, const StaticOrder& S, const Epi& E) {
;     ...
;         const char* nA = has_next ? (const char*)g.A + (size_t)nxt.pm * tstepA : cA; const char* nB = has_next ? (const char*)g.Bt + (size_t)nxt.pn * tstepB : cB;
;         for (int t = 0; t < nt; t += 2) {
;             const bool last = (t == nt - 2);
;             const char* a1 = cA + (size_t)(t + 1) * kstep;
;             const char* a2 = last ? nA : cA + (size_t)(t + 2) * kstep; const char* b2 = last ? nB : cB + (size_t)(t + 2) * kstep;
;             const char* a3 = a2 + kstep; const char* b3 = b2 + kstep;
;     ...
; #pragma unroll
;         for (int a = 0; a < 2; ++a)
; #pragma unroll
;             for (int b = 0; b < 2; ++b)
; #pragma unroll
;                 for (int m = 0; m < 4; ++m)
; #pragma unroll
;                     for (int n = 0; n < 2; ++n) acc[a][b][m][n] = (f32x4){0.f, 0.f, 0.f, 0.f};
.LBB0_267:
	s_ashr_i32 s35, s34, 31
	s_lshl_b64 s[20:21], s[34:35], 19
	s_add_u32 s36, s42, s20
	s_addc_u32 s37, s43, s21
	s_and_b64 s[20:21], s[0:1], exec
	s_cselect_b32 s17, s37, s41
	s_cselect_b32 s35, s36, s40
	s_ashr_i32 s23, s22, 31
	s_lshl_b64 s[20:21], s[22:23], 19
	s_add_u32 s38, s90, s20
	s_addc_u32 s39, s33, s21
	s_and_b64 s[20:21], s[0:1], exec
	s_cselect_b32 s23, s39, s53
	s_cselect_b32 s46, s38, s52
	s_add_u32 s40, s40, 0x40080
	s_addc_u32 s41, s41, 0
	s_add_u32 s47, s52, 0x100
	v_mov_b32_e32 v0, 0
	s_addc_u32 s78, s53, 0
	s_mov_b32 s79, -2
	v_mov_b32_e32 v1, v0
	v_pk_mov_b32 v[2:3], v[0:1], v[0:1]
	v_pk_mov_b32 v[4:5], v[0:1], v[0:1]
	v_pk_mov_b32 v[6:7], v[0:1], v[0:1]
	v_pk_mov_b32 v[8:9], v[0:1], v[0:1]
	v_pk_mov_b32 v[10:11], v[0:1], v[0:1]
	v_pk_mov_b32 v[12:13], v[0:1], v[0:1]
	v_pk_mov_b32 v[14:15], v[0:1], v[0:1]
	v_pk_mov_b32 v[16:17], v[0:1], v[0:1]
	v_pk_mov_b32 v[18:19], v[0:1], v[0:1]
	v_pk_mov_b32 v[20:21], v[0:1], v[0:1]
	v_pk_mov_b32 v[22:23], v[0:1], v[0:1]
	v_pk_mov_b32 v[24:25], v[0:1], v[0:1]
	v_pk_mov_b32 v[26:27], v[0:1], v[0:1]
	v_pk_mov_b32 v[28:29], v[0:1], v[0:1]
	v_pk_mov_b32 v[30:31], v[0:1], v[0:1]
	v_pk_mov_b32 v[32:33], v[0:1], v[0:1]
	v_pk_mov_b32 v[34:35], v[0:1], v[0:1]
	v_pk_mov_b32 v[36:37], v[0:1], v[0:1]
	v_pk_mov_b32 v[38:39], v[0:1], v[0:1]
	v_pk_mov_b32 v[40:41], v[0:1], v[0:1]
	v_pk_mov_b32 v[42:43], v[0:1], v[0:1]
	v_pk_mov_b32 v[44:45], v[0:1], v[0:1]
	v_pk_mov_b32 v[46:47], v[0:1], v[0:1]
	v_pk_mov_b32 v[48:49], v[0:1], v[0:1]
	v_pk_mov_b32 v[50:51], v[0:1], v[0:1]
	v_pk_mov_b32 v[52:53], v[0:1], v[0:1]
	v_pk_mov_b32 v[54:55], v[0:1], v[0:1]
	v_pk_mov_b32 v[56:57], v[0:1], v[0:1]
	v_pk_mov_b32 v[58:59], v[0:1], v[0:1]
	v_pk_mov_b32 v[60:61], v[0:1], v[0:1]
	v_pk_mov_b32 v[62:63], v[0:1], v[0:1]
	v_pk_mov_b32 v[64:65], v[0:1], v[0:1]
	v_pk_mov_b32 v[66:67], v[0:1], v[0:1]
	v_pk_mov_b32 v[68:69], v[0:1], v[0:1]
	v_pk_mov_b32 v[70:71], v[0:1], v[0:1]
	v_pk_mov_b32 v[88:89], v[0:1], v[0:1]
	v_pk_mov_b32 v[90:91], v[0:1], v[0:1]
	v_pk_mov_b32 v[92:93], v[0:1], v[0:1]
	v_pk_mov_b32 v[94:95], v[0:1], v[0:1]
	v_pk_mov_b32 v[96:97], v[0:1], v[0:1]
	v_pk_mov_b32 v[98:99], v[0:1], v[0:1]
	v_pk_mov_b32 v[100:101], v[0:1], v[0:1]
	v_pk_mov_b32 v[102:103], v[0:1], v[0:1]
	v_pk_mov_b32 v[104:105], v[0:1], v[0:1]
	v_pk_mov_b32 v[106:107], v[0:1], v[0:1]
	v_pk_mov_b32 v[108:109], v[0:1], v[0:1]
	v_pk_mov_b32 v[110:111], v[0:1], v[0:1]
	v_pk_mov_b32 v[112:113], v[0:1], v[0:1]
	v_pk_mov_b32 v[114:115], v[0:1], v[0:1]
	v_pk_mov_b32 v[116:117], v[0:1], v[0:1]
	v_pk_mov_b32 v[118:119], v[0:1], v[0:1]
	v_pk_mov_b32 v[120:121], v[0:1], v[0:1]
	v_pk_mov_b32 v[122:123], v[0:1], v[0:1]
	v_pk_mov_b32 v[124:125], v[0:1], v[0:1]
	v_pk_mov_b32 v[126:127], v[0:1], v[0:1]
	v_pk_mov_b32 v[128:129], v[0:1], v[0:1]
	v_pk_mov_b32 v[130:131], v[0:1], v[0:1]
	v_pk_mov_b32 v[132:133], v[0:1], v[0:1]
	v_pk_mov_b32 v[134:135], v[0:1], v[0:1]
	v_pk_mov_b32 v[136:137], v[0:1], v[0:1]
	v_pk_mov_b32 v[138:139], v[0:1], v[0:1]
	v_pk_mov_b32 v[140:141], v[0:1], v[0:1]
	v_pk_mov_b32 v[142:143], v[0:1], v[0:1]

; template <class Epi>
; __device__ __forceinline__ void gemm_phase(LAS unsigned char* lds, const Gemm g, const StaticOrder& S, const Epi& E) {
;     ...
;             const char* a1 = cA + (size_t)(t + 1) * kstep;
;             const char* a2 = last ? nA : cA + (size_t)(t + 2) * kstep; const char* b2 = last ? nB : cB + (size_t)(t + 2) * kstep;
;     ...
; #pragma unroll
;         for (int a = 0; a < 2; ++a)
; #pragma unroll
;             for (int b = 0; b < 2; ++b)
; #pragma unroll
;                 for (int m = 0; m < 4; ++m)
; #pragma unroll
;                     for (int n = 0; n < 2; ++n) acc[a][b][m][n] = (f32x4){0.f, 0.f, 0.f, 0.f};
.LBB0_359:
	s_add_u32 s46, s60, 0x100
	v_mov_b32_e32 v0, 0
	s_addc_u32 s47, s61, 0
	s_mov_b32 vcc_lo, -2
	v_mov_b32_e32 v1, v0
	v_pk_mov_b32 v[2:3], v[0:1], v[0:1]
	v_pk_mov_b32 v[4:5], v[0:1], v[0:1]
	v_pk_mov_b32 v[6:7], v[0:1], v[0:1]
	v_pk_mov_b32 v[8:9], v[0:1], v[0:1]
	v_pk_mov_b32 v[10:11], v[0:1], v[0:1]
	v_pk_mov_b32 v[12:13], v[0:1], v[0:1]
	v_pk_mov_b32 v[14:15], v[0:1], v[0:1]
	v_pk_mov_b32 v[16:17], v[0:1], v[0:1]
	v_pk_mov_b32 v[18:19], v[0:1], v[0:1]
	v_pk_mov_b32 v[20:21], v[0:1], v[0:1]
	v_pk_mov_b32 v[22:23], v[0:1], v[0:1]
	v_pk_mov_b32 v[24:25], v[0:1], v[0:1]
	v_pk_mov_b32 v[26:27], v[0:1], v[0:1]
	v_pk_mov_b32 v[28:29], v[0:1], v[0:1]
	v_pk_mov_b32 v[30:31], v[0:1], v[0:1]
	v_pk_mov_b32 v[32:33], v[0:1], v[0:1]
	v_pk_mov_b32 v[34:35], v[0:1], v[0:1]
	v_pk_mov_b32 v[36:37], v[0:1], v[0:1]
	v_pk_mov_b32 v[38:39], v[0:1], v[0:1]
	v_pk_mov_b32 v[40:41], v[0:1], v[0:1]
	v_pk_mov_b32 v[42:43], v[0:1], v[0:1]
	v_pk_mov_b32 v[44:45], v[0:1], v[0:1]
	v_pk_mov_b32 v[46:47], v[0:1], v[0:1]
	v_pk_mov_b32 v[48:49], v[0:1], v[0:1]
	v_pk_mov_b32 v[50:51], v[0:1], v[0:1]
	v_pk_mov_b32 v[52:53], v[0:1], v[0:1]
	v_pk_mov_b32 v[54:55], v[0:1], v[0:1]
	v_pk_mov_b32 v[56:57], v[0:1], v[0:1]
	v_pk_mov_b32 v[58:59], v[0:1], v[0:1]
	v_pk_mov_b32 v[84:85], v[0:1], v[0:1]
	v_pk_mov_b32 v[86:87], v[0:1], v[0:1]
	v_pk_mov_b32 v[96:97], v[0:1], v[0:1]
	v_pk_mov_b32 v[98:99], v[0:1], v[0:1]
	v_pk_mov_b32 v[100:101], v[0:1], v[0:1]
	v_pk_mov_b32 v[102:103], v[0:1], v[0:1]
	v_pk_mov_b32 v[104:105], v[0:1], v[0:1]
	v_pk_mov_b32 v[106:107], v[0:1], v[0:1]
	v_pk_mov_b32 v[108:109], v[0:1], v[0:1]
	v_pk_mov_b32 v[110:111], v[0:1], v[0:1]
	v_pk_mov_b32 v[112:113], v[0:1], v[0:1]
	v_pk_mov_b32 v[114:115], v[0:1], v[0:1]
	v_pk_mov_b32 v[116:117], v[0:1], v[0:1]
	v_pk_mov_b32 v[118:119], v[0:1], v[0:1]
	v_pk_mov_b32 v[120:121], v[0:1], v[0:1]
	v_pk_mov_b32 v[122:123], v[0:1], v[0:1]
	v_pk_mov_b32 v[124:125], v[0:1], v[0:1]
	v_pk_mov_b32 v[126:127], v[0:1], v[0:1]
	v_pk_mov_b32 v[128:129], v[0:1], v[0:1]
	v_pk_mov_b32 v[130:131], v[0:1], v[0:1]
	v_pk_mov_b32 v[132:133], v[0:1], v[0:1]
	v_pk_mov_b32 v[134:135], v[0:1], v[0:1]
	v_pk_mov_b32 v[136:137], v[0:1], v[0:1]
	v_pk_mov_b32 v[138:139], v[0:1], v[0:1]
	v_pk_mov_b32 v[140:141], v[0:1], v[0:1]
	v_pk_mov_b32 v[142:143], v[0:1], v[0:1]
	v_pk_mov_b32 v[144:145], v[0:1], v[0:1]
	v_pk_mov_b32 v[146:147], v[0:1], v[0:1]
	v_pk_mov_b32 v[148:149], v[0:1], v[0:1]
	v_pk_mov_b32 v[150:151], v[0:1], v[0:1]
	v_pk_mov_b32 v[152:153], v[0:1], v[0:1]
	v_pk_mov_b32 v[154:155], v[0:1], v[0:1]
	v_pk_mov_b32 v[156:157], v[0:1], v[0:1]
	v_pk_mov_b32 v[158:159], v[0:1], v[0:1]

; template <class Epi>
; __device__ __forceinline__ void gemm_phase(LAS unsigned char* lds, const Gemm g, const StaticOrder& S, const Epi& E) {
;     ...
;         const char* nA = has_next ? (const char*)g.A + (size_t)nxt.pm * tstepA : cA; const char* nB = has_next ? (const char*)g.Bt + (size_t)nxt.pn * tstepB : cB;
;         for (int t = 0; t < nt; t += 2) {
;             const bool last = (t == nt - 2);
;             const char* a1 = cA + (size_t)(t + 1) * kstep;
;             const char* a2 = last ? nA : cA + (size_t)(t + 2) * kstep; const char* b2 = last ? nB : cB + (size_t)(t + 2) * kstep;
;             const char* a3 = a2 + kstep; const char* b3 = b2 + kstep;
;     ...
; #pragma unroll
;         for (int a = 0; a < 2; ++a)
; #pragma unroll
;             for (int b = 0; b < 2; ++b)
; #pragma unroll
;                 for (int m = 0; m < 4; ++m)
; #pragma unroll
;                     for (int n = 0; n < 2; ++n) acc[a][b][m][n] = (f32x4){0.f, 0.f, 0.f, 0.f};
.LBB0_451:
	s_ashr_i32 s35, s34, 31
	s_lshl_b64 s[20:21], s[34:35], 19
	s_add_u32 s36, s42, s20
	s_addc_u32 s37, s43, s21
	s_and_b64 s[20:21], s[0:1], exec
	s_cselect_b32 s17, s37, s41
	s_cselect_b32 s35, s36, s40
	s_ashr_i32 s13, s12, 31
	s_lshl_b64 s[20:21], s[12:13], 19
	s_add_u32 s38, s14, s20
	s_addc_u32 s39, s15, s21
	s_and_b64 s[20:21], s[0:1], exec
	s_cselect_b32 s13, s39, s53
	s_cselect_b32 s46, s38, s52
	s_add_u32 s40, s40, 0x40080
	s_addc_u32 s41, s41, 0
	s_add_u32 s47, s52, 0x100
	v_mov_b32_e32 v0, 0
	s_addc_u32 s81, s53, 0
	s_mov_b32 s82, -2
	v_mov_b32_e32 v1, v0
	v_pk_mov_b32 v[2:3], v[0:1], v[0:1]
	v_pk_mov_b32 v[4:5], v[0:1], v[0:1]
	v_pk_mov_b32 v[6:7], v[0:1], v[0:1]
	v_pk_mov_b32 v[8:9], v[0:1], v[0:1]
	v_pk_mov_b32 v[10:11], v[0:1], v[0:1]
	v_pk_mov_b32 v[12:13], v[0:1], v[0:1]
	v_pk_mov_b32 v[14:15], v[0:1], v[0:1]
	v_pk_mov_b32 v[16:17], v[0:1], v[0:1]
	v_pk_mov_b32 v[18:19], v[0:1], v[0:1]
	v_pk_mov_b32 v[20:21], v[0:1], v[0:1]
	v_pk_mov_b32 v[22:23], v[0:1], v[0:1]
	v_pk_mov_b32 v[24:25], v[0:1], v[0:1]
	v_pk_mov_b32 v[26:27], v[0:1], v[0:1]
	v_pk_mov_b32 v[28:29], v[0:1], v[0:1]
	v_pk_mov_b32 v[30:31], v[0:1], v[0:1]
	v_pk_mov_b32 v[32:33], v[0:1], v[0:1]
	v_pk_mov_b32 v[34:35], v[0:1], v[0:1]
	v_pk_mov_b32 v[36:37], v[0:1], v[0:1]
	v_pk_mov_b32 v[38:39], v[0:1], v[0:1]
	v_pk_mov_b32 v[40:41], v[0:1], v[0:1]
	v_pk_mov_b32 v[42:43], v[0:1], v[0:1]
	v_pk_mov_b32 v[44:45], v[0:1], v[0:1]
	v_pk_mov_b32 v[46:47], v[0:1], v[0:1]
	v_pk_mov_b32 v[48:49], v[0:1], v[0:1]
	v_pk_mov_b32 v[50:51], v[0:1], v[0:1]
	v_pk_mov_b32 v[52:53], v[0:1], v[0:1]
	v_pk_mov_b32 v[54:55], v[0:1], v[0:1]
	v_pk_mov_b32 v[56:57], v[0:1], v[0:1]
	v_pk_mov_b32 v[58:59], v[0:1], v[0:1]
	v_pk_mov_b32 v[60:61], v[0:1], v[0:1]
	v_pk_mov_b32 v[62:63], v[0:1], v[0:1]
	v_pk_mov_b32 v[64:65], v[0:1], v[0:1]
	v_pk_mov_b32 v[66:67], v[0:1], v[0:1]
	v_pk_mov_b32 v[68:69], v[0:1], v[0:1]
	v_pk_mov_b32 v[70:71], v[0:1], v[0:1]
	v_pk_mov_b32 v[72:73], v[0:1], v[0:1]
	v_pk_mov_b32 v[74:75], v[0:1], v[0:1]
	v_pk_mov_b32 v[76:77], v[0:1], v[0:1]
	v_pk_mov_b32 v[78:79], v[0:1], v[0:1]
	v_pk_mov_b32 v[80:81], v[0:1], v[0:1]
	v_pk_mov_b32 v[82:83], v[0:1], v[0:1]
	v_pk_mov_b32 v[84:85], v[0:1], v[0:1]
	v_pk_mov_b32 v[86:87], v[0:1], v[0:1]
	v_pk_mov_b32 v[88:89], v[0:1], v[0:1]
	v_pk_mov_b32 v[90:91], v[0:1], v[0:1]
	v_pk_mov_b32 v[92:93], v[0:1], v[0:1]
	v_pk_mov_b32 v[94:95], v[0:1], v[0:1]
	v_pk_mov_b32 v[96:97], v[0:1], v[0:1]
	v_pk_mov_b32 v[98:99], v[0:1], v[0:1]
	v_pk_mov_b32 v[100:101], v[0:1], v[0:1]
	v_pk_mov_b32 v[102:103], v[0:1], v[0:1]
	v_pk_mov_b32 v[104:105], v[0:1], v[0:1]
	v_pk_mov_b32 v[106:107], v[0:1], v[0:1]
	v_pk_mov_b32 v[108:109], v[0:1], v[0:1]
	v_pk_mov_b32 v[110:111], v[0:1], v[0:1]
	v_pk_mov_b32 v[112:113], v[0:1], v[0:1]
	v_pk_mov_b32 v[114:115], v[0:1], v[0:1]
	v_pk_mov_b32 v[116:117], v[0:1], v[0:1]
	v_pk_mov_b32 v[118:119], v[0:1], v[0:1]
	v_pk_mov_b32 v[120:121], v[0:1], v[0:1]
	v_pk_mov_b32 v[122:123], v[0:1], v[0:1]
	v_pk_mov_b32 v[124:125], v[0:1], v[0:1]
	v_pk_mov_b32 v[126:127], v[0:1], v[0:1]

; template <class Epi>
; __device__ __forceinline__ void gemm_phase(LAS unsigned char* lds, const Gemm g, const StaticOrder& S, const Epi& E) {
;     ...
;             const char* a1 = cA + (size_t)(t + 1) * kstep;
;             const char* a2 = last ? nA : cA + (size_t)(t + 2) * kstep; const char* b2 = last ? nB : cB + (size_t)(t + 2) * kstep;
;     ...
; #pragma unroll
;         for (int a = 0; a < 2; ++a)
; #pragma unroll
;             for (int b = 0; b < 2; ++b)
; #pragma unroll
;                 for (int m = 0; m < 4; ++m)
; #pragma unroll
;                     for (int n = 0; n < 2; ++n) acc[a][b][m][n] = (f32x4){0.f, 0.f, 0.f, 0.f};
.LBB0_608:
	s_add_u32 s46, s38, 0x100
	v_mov_b32_e32 v0, 0
	s_addc_u32 s47, s39, 0
	s_mov_b32 s78, -2
	v_mov_b32_e32 v1, v0
	v_pk_mov_b32 v[2:3], v[0:1], v[0:1]
	v_pk_mov_b32 v[4:5], v[0:1], v[0:1]
	v_pk_mov_b32 v[6:7], v[0:1], v[0:1]
	v_pk_mov_b32 v[8:9], v[0:1], v[0:1]
	v_pk_mov_b32 v[10:11], v[0:1], v[0:1]
	v_pk_mov_b32 v[12:13], v[0:1], v[0:1]
	v_pk_mov_b32 v[14:15], v[0:1], v[0:1]
	v_pk_mov_b32 v[16:17], v[0:1], v[0:1]
	v_pk_mov_b32 v[18:19], v[0:1], v[0:1]
	v_pk_mov_b32 v[20:21], v[0:1], v[0:1]
	v_pk_mov_b32 v[22:23], v[0:1], v[0:1]
	v_pk_mov_b32 v[24:25], v[0:1], v[0:1]
	v_pk_mov_b32 v[26:27], v[0:1], v[0:1]
	v_pk_mov_b32 v[28:29], v[0:1], v[0:1]
	v_pk_mov_b32 v[30:31], v[0:1], v[0:1]
	v_pk_mov_b32 v[32:33], v[0:1], v[0:1]
	v_pk_mov_b32 v[34:35], v[0:1], v[0:1]
	v_pk_mov_b32 v[36:37], v[0:1], v[0:1]
	v_pk_mov_b32 v[38:39], v[0:1], v[0:1]
	v_pk_mov_b32 v[40:41], v[0:1], v[0:1]
	v_pk_mov_b32 v[42:43], v[0:1], v[0:1]
	v_pk_mov_b32 v[44:45], v[0:1], v[0:1]
	v_pk_mov_b32 v[46:47], v[0:1], v[0:1]
	v_pk_mov_b32 v[48:49], v[0:1], v[0:1]
	v_pk_mov_b32 v[50:51], v[0:1], v[0:1]
	v_pk_mov_b32 v[52:53], v[0:1], v[0:1]
	v_pk_mov_b32 v[54:55], v[0:1], v[0:1]
	v_pk_mov_b32 v[56:57], v[0:1], v[0:1]
	v_pk_mov_b32 v[58:59], v[0:1], v[0:1]
	v_pk_mov_b32 v[60:61], v[0:1], v[0:1]
	v_pk_mov_b32 v[62:63], v[0:1], v[0:1]
	v_pk_mov_b32 v[64:65], v[0:1], v[0:1]
	v_pk_mov_b32 v[66:67], v[0:1], v[0:1]
	v_pk_mov_b32 v[68:69], v[0:1], v[0:1]
	v_pk_mov_b32 v[70:71], v[0:1], v[0:1]
	v_pk_mov_b32 v[72:73], v[0:1], v[0:1]
	v_pk_mov_b32 v[74:75], v[0:1], v[0:1]
	v_pk_mov_b32 v[76:77], v[0:1], v[0:1]
	v_pk_mov_b32 v[78:79], v[0:1], v[0:1]
	v_pk_mov_b32 v[80:81], v[0:1], v[0:1]
	v_pk_mov_b32 v[82:83], v[0:1], v[0:1]
	v_pk_mov_b32 v[84:85], v[0:1], v[0:1]
	v_pk_mov_b32 v[86:87], v[0:1], v[0:1]
	v_pk_mov_b32 v[88:89], v[0:1], v[0:1]
	v_pk_mov_b32 v[90:91], v[0:1], v[0:1]
	v_pk_mov_b32 v[92:93], v[0:1], v[0:1]
	v_pk_mov_b32 v[94:95], v[0:1], v[0:1]
	v_pk_mov_b32 v[96:97], v[0:1], v[0:1]
	v_pk_mov_b32 v[98:99], v[0:1], v[0:1]
	v_pk_mov_b32 v[100:101], v[0:1], v[0:1]
	v_pk_mov_b32 v[102:103], v[0:1], v[0:1]
	v_pk_mov_b32 v[104:105], v[0:1], v[0:1]
	v_pk_mov_b32 v[106:107], v[0:1], v[0:1]
	v_pk_mov_b32 v[108:109], v[0:1], v[0:1]
	v_pk_mov_b32 v[110:111], v[0:1], v[0:1]
	v_pk_mov_b32 v[112:113], v[0:1], v[0:1]
	v_pk_mov_b32 v[114:115], v[0:1], v[0:1]
	v_pk_mov_b32 v[116:117], v[0:1], v[0:1]
	v_pk_mov_b32 v[118:119], v[0:1], v[0:1]
	v_pk_mov_b32 v[120:121], v[0:1], v[0:1]
	v_pk_mov_b32 v[122:123], v[0:1], v[0:1]
	v_pk_mov_b32 v[124:125], v[0:1], v[0:1]
	v_pk_mov_b32 v[126:127], v[0:1], v[0:1]

; template <class Epi>
; __device__ __forceinline__ void gemm_phase(LAS unsigned char* lds, const Gemm g, const StaticOrder& S, const Epi& E) {
;     ...
;         const char* nA = has_next ? (const char*)g.A + (size_t)nxt.pm * tstepA : cA; const char* nB = has_next ? (const char*)g.Bt + (size_t)nxt.pn * tstepB : cB;
;         for (int t = 0; t < nt; t += 2) {
;             const bool last = (t == nt - 2);
;             const char* a1 = cA + (size_t)(t + 1) * kstep;
;             const char* a2 = last ? nA : cA + (size_t)(t + 2) * kstep; const char* b2 = last ? nB : cB + (size_t)(t + 2) * kstep;
;             const char* a3 = a2 + kstep; const char* b3 = b2 + kstep;
;     ...
; #pragma unroll
;         for (int a = 0; a < 2; ++a)
; #pragma unroll
;             for (int b = 0; b < 2; ++b)
; #pragma unroll
;                 for (int m = 0; m < 4; ++m)
; #pragma unroll
;                     for (int n = 0; n < 2; ++n) acc[a][b][m][n] = (f32x4){0.f, 0.f, 0.f, 0.f};
.LBB0_624:
	s_ashr_i32 s17, s16, 31
	s_lshl_b64 s[20:21], s[16:17], 17
	s_add_u32 s26, s22, s20
	s_addc_u32 s27, s23, s21
	s_and_b64 s[20:21], s[0:1], exec
	s_cselect_b32 s17, s27, s41
	s_cselect_b32 s46, s26, s40
	s_ashr_i32 s15, s14, 31
	s_lshl_b64 s[20:21], s[14:15], 17
	s_add_u32 s38, s48, s20
	s_addc_u32 s39, s49, s21
	s_and_b64 s[20:21], s[0:1], exec
	v_mov_b32_e32 v0, 0
	s_cselect_b32 s15, s39, s37
	s_cselect_b32 s47, s38, s36
	s_mov_b32 s58, 0
	s_mov_b64 s[52:53], -1
	s_mov_b64 s[56:57], 0
	v_mov_b32_e32 v1, v0
	v_pk_mov_b32 v[2:3], v[0:1], v[0:1]
	v_pk_mov_b32 v[4:5], v[0:1], v[0:1]
	v_pk_mov_b32 v[6:7], v[0:1], v[0:1]
	v_pk_mov_b32 v[8:9], v[0:1], v[0:1]
	v_pk_mov_b32 v[10:11], v[0:1], v[0:1]
	v_pk_mov_b32 v[12:13], v[0:1], v[0:1]
	v_pk_mov_b32 v[14:15], v[0:1], v[0:1]
	v_pk_mov_b32 v[16:17], v[0:1], v[0:1]
	v_pk_mov_b32 v[18:19], v[0:1], v[0:1]
	v_pk_mov_b32 v[20:21], v[0:1], v[0:1]
	v_pk_mov_b32 v[22:23], v[0:1], v[0:1]
	v_pk_mov_b32 v[24:25], v[0:1], v[0:1]
	v_pk_mov_b32 v[26:27], v[0:1], v[0:1]
	v_pk_mov_b32 v[28:29], v[0:1], v[0:1]
	v_pk_mov_b32 v[30:31], v[0:1], v[0:1]
	v_pk_mov_b32 v[32:33], v[0:1], v[0:1]
	v_pk_mov_b32 v[34:35], v[0:1], v[0:1]
	v_pk_mov_b32 v[36:37], v[0:1], v[0:1]
	v_pk_mov_b32 v[38:39], v[0:1], v[0:1]
	v_pk_mov_b32 v[40:41], v[0:1], v[0:1]
	v_pk_mov_b32 v[42:43], v[0:1], v[0:1]
	v_pk_mov_b32 v[44:45], v[0:1], v[0:1]
	v_pk_mov_b32 v[46:47], v[0:1], v[0:1]
	v_pk_mov_b32 v[48:49], v[0:1], v[0:1]
	v_pk_mov_b32 v[50:51], v[0:1], v[0:1]
	v_pk_mov_b32 v[52:53], v[0:1], v[0:1]
	v_pk_mov_b32 v[54:55], v[0:1], v[0:1]
	v_pk_mov_b32 v[56:57], v[0:1], v[0:1]
	v_pk_mov_b32 v[58:59], v[0:1], v[0:1]
	v_pk_mov_b32 v[60:61], v[0:1], v[0:1]
	v_pk_mov_b32 v[62:63], v[0:1], v[0:1]
	v_pk_mov_b32 v[64:65], v[0:1], v[0:1]
	v_pk_mov_b32 v[66:67], v[0:1], v[0:1]
	v_pk_mov_b32 v[68:69], v[0:1], v[0:1]
	v_pk_mov_b32 v[70:71], v[0:1], v[0:1]
	v_pk_mov_b32 v[72:73], v[0:1], v[0:1]
	v_pk_mov_b32 v[74:75], v[0:1], v[0:1]
	v_pk_mov_b32 v[76:77], v[0:1], v[0:1]
	v_pk_mov_b32 v[78:79], v[0:1], v[0:1]
	v_pk_mov_b32 v[80:81], v[0:1], v[0:1]
	v_pk_mov_b32 v[82:83], v[0:1], v[0:1]
	v_pk_mov_b32 v[84:85], v[0:1], v[0:1]
	v_pk_mov_b32 v[86:87], v[0:1], v[0:1]
	v_pk_mov_b32 v[88:89], v[0:1], v[0:1]
	v_pk_mov_b32 v[90:91], v[0:1], v[0:1]
	v_pk_mov_b32 v[92:93], v[0:1], v[0:1]
	v_pk_mov_b32 v[94:95], v[0:1], v[0:1]
	v_pk_mov_b32 v[96:97], v[0:1], v[0:1]
	v_pk_mov_b32 v[98:99], v[0:1], v[0:1]
	v_pk_mov_b32 v[100:101], v[0:1], v[0:1]
	v_pk_mov_b32 v[102:103], v[0:1], v[0:1]
	v_pk_mov_b32 v[104:105], v[0:1], v[0:1]
	v_pk_mov_b32 v[106:107], v[0:1], v[0:1]
	v_pk_mov_b32 v[108:109], v[0:1], v[0:1]
	v_pk_mov_b32 v[110:111], v[0:1], v[0:1]
	v_pk_mov_b32 v[112:113], v[0:1], v[0:1]
	v_pk_mov_b32 v[114:115], v[0:1], v[0:1]
	v_pk_mov_b32 v[116:117], v[0:1], v[0:1]
	v_pk_mov_b32 v[118:119], v[0:1], v[0:1]
	v_pk_mov_b32 v[120:121], v[0:1], v[0:1]
	v_pk_mov_b32 v[122:123], v[0:1], v[0:1]
	v_pk_mov_b32 v[124:125], v[0:1], v[0:1]
	v_pk_mov_b32 v[126:127], v[0:1], v[0:1]

; template <class Epi>
; __device__ __forceinline__ void gemm_phase(LAS unsigned char* lds, const Gemm g, const StaticOrder& S, const Epi& E) {
;     ...
;         const char* nA = has_next ? (const char*)g.A + (size_t)nxt.pm * tstepA : cA; const char* nB = has_next ? (const char*)g.Bt + (size_t)nxt.pn * tstepB : cB;
;         for (int t = 0; t < nt; t += 2) {
;             const bool last = (t == nt - 2);
;             const char* a1 = cA + (size_t)(t + 1) * kstep;
;             const char* a2 = last ? nA : cA + (size_t)(t + 2) * kstep; const char* b2 = last ? nB : cB + (size_t)(t + 2) * kstep;
;             const char* a3 = a2 + kstep; const char* b3 = b2 + kstep;
;     ...
; #pragma unroll
;         for (int a = 0; a < 2; ++a)
; #pragma unroll
;             for (int b = 0; b < 2; ++b)
; #pragma unroll
;                 for (int m = 0; m < 4; ++m)
; #pragma unroll
;                     for (int n = 0; n < 2; ++n) acc[a][b][m][n] = (f32x4){0.f, 0.f, 0.f, 0.f};
.LBB0_1629:
	s_ashr_i32 s41, s40, 31
	s_lshl_b64 s[46:47], s[40:41], 19
	s_add_u32 s52, s54, s46
	s_addc_u32 s53, s55, s47
	s_and_b64 s[46:47], s[20:21], exec
	s_cselect_b32 s41, s53, s63
	s_cselect_b32 s46, s52, s62
	s_ashr_i32 s39, s38, 31
	s_lshl_b64 s[56:57], s[38:39], 19
	s_add_u32 s56, s26, s56
	s_addc_u32 s57, s27, s57
	s_and_b64 s[68:69], s[20:21], exec
	s_cselect_b32 s39, s57, s65
	s_cselect_b32 s47, s56, s64
	s_add_u32 s62, s62, 0x40080
	s_addc_u32 s63, s63, 0
	s_add_u32 s59, s64, 0x100
	v_mov_b32_e32 v0, 0
	s_addc_u32 s61, s65, 0
	s_mov_b32 s79, -2
	v_mov_b32_e32 v1, v0
	v_mov_b32_e32 v2, v0
	v_mov_b32_e32 v3, v0
	v_mov_b32_e32 v4, v0
	v_mov_b32_e32 v5, v0
	v_mov_b32_e32 v6, v0
	v_mov_b32_e32 v7, v0
	v_mov_b32_e32 v16, v0
	v_mov_b32_e32 v17, v0
	v_mov_b32_e32 v18, v0
	v_mov_b32_e32 v19, v0
	v_mov_b32_e32 v20, v0
	v_mov_b32_e32 v21, v0
	v_mov_b32_e32 v22, v0
	v_mov_b32_e32 v23, v0
	v_mov_b32_e32 v32, v0
	v_mov_b32_e32 v33, v0
	s_waitcnt vmcnt(0)
	v_pk_mov_b32 v[8:9], v[0:1], v[0:1]
	v_pk_mov_b32 v[10:11], v[0:1], v[0:1]
	v_pk_mov_b32 v[12:13], v[0:1], v[0:1]
	v_pk_mov_b32 v[14:15], v[0:1], v[0:1]
	v_pk_mov_b32 v[24:25], v[0:1], v[0:1]
	v_pk_mov_b32 v[26:27], v[0:1], v[0:1]
	v_pk_mov_b32 v[28:29], v[0:1], v[0:1]
	v_pk_mov_b32 v[30:31], v[0:1], v[0:1]
	v_pk_mov_b32 v[34:35], v[0:1], v[0:1]
	v_pk_mov_b32 v[36:37], v[0:1], v[0:1]
	v_pk_mov_b32 v[38:39], v[0:1], v[0:1]
	v_pk_mov_b32 v[40:41], v[0:1], v[0:1]
	v_pk_mov_b32 v[42:43], v[0:1], v[0:1]
	v_pk_mov_b32 v[44:45], v[0:1], v[0:1]
	v_pk_mov_b32 v[46:47], v[0:1], v[0:1]
	v_pk_mov_b32 v[48:49], v[0:1], v[0:1]
	v_pk_mov_b32 v[50:51], v[0:1], v[0:1]
	v_pk_mov_b32 v[52:53], v[0:1], v[0:1]
	v_pk_mov_b32 v[54:55], v[0:1], v[0:1]
	v_pk_mov_b32 v[56:57], v[0:1], v[0:1]
	v_pk_mov_b32 v[58:59], v[0:1], v[0:1]
	v_pk_mov_b32 v[60:61], v[0:1], v[0:1]
	v_pk_mov_b32 v[62:63], v[0:1], v[0:1]
	v_pk_mov_b32 v[112:113], v[0:1], v[0:1]
	v_pk_mov_b32 v[114:115], v[0:1], v[0:1]
	v_pk_mov_b32 v[116:117], v[0:1], v[0:1]
	v_pk_mov_b32 v[118:119], v[0:1], v[0:1]
	v_pk_mov_b32 v[120:121], v[0:1], v[0:1]
	v_pk_mov_b32 v[122:123], v[0:1], v[0:1]
	v_pk_mov_b32 v[124:125], v[0:1], v[0:1]
	v_pk_mov_b32 v[126:127], v[0:1], v[0:1]
	v_pk_mov_b32 v[128:129], v[0:1], v[0:1]
	v_pk_mov_b32 v[130:131], v[0:1], v[0:1]
	v_pk_mov_b32 v[132:133], v[0:1], v[0:1]
	v_pk_mov_b32 v[134:135], v[0:1], v[0:1]
	v_pk_mov_b32 v[136:137], v[0:1], v[0:1]
	v_pk_mov_b32 v[138:139], v[0:1], v[0:1]
	v_pk_mov_b32 v[140:141], v[0:1], v[0:1]
	v_pk_mov_b32 v[142:143], v[0:1], v[0:1]
	v_pk_mov_b32 v[144:145], v[0:1], v[0:1]
	v_pk_mov_b32 v[146:147], v[0:1], v[0:1]
	v_pk_mov_b32 v[148:149], v[0:1], v[0:1]
	v_pk_mov_b32 v[150:151], v[0:1], v[0:1]
	v_pk_mov_b32 v[152:153], v[0:1], v[0:1]
	v_pk_mov_b32 v[154:155], v[0:1], v[0:1]
	v_pk_mov_b32 v[156:157], v[0:1], v[0:1]
	v_pk_mov_b32 v[158:159], v[0:1], v[0:1]
	v_pk_mov_b32 v[160:161], v[0:1], v[0:1]
	v_pk_mov_b32 v[162:163], v[0:1], v[0:1]
	v_pk_mov_b32 v[164:165], v[0:1], v[0:1]
	v_pk_mov_b32 v[166:167], v[0:1], v[0:1]
	v_pk_mov_b32 v[168:169], v[0:1], v[0:1]
	v_pk_mov_b32 v[170:171], v[0:1], v[0:1]
	v_pk_mov_b32 v[172:173], v[0:1], v[0:1]
	v_pk_mov_b32 v[174:175], v[0:1], v[0:1]

; template <class Epi>
; __device__ __forceinline__ void gemm_phase(LAS unsigned char* lds, const Gemm g, const StaticOrder& S, const Epi& E) {
;     ...
;         const char* nA = has_next ? (const char*)g.A + (size_t)nxt.pm * tstepA : cA; const char* nB = has_next ? (const char*)g.Bt + (size_t)nxt.pn * tstepB : cB;
;         for (int t = 0; t < nt; t += 2) {
;             const bool last = (t == nt - 2);
;             const char* a1 = cA + (size_t)(t + 1) * kstep;
;             const char* a2 = last ? nA : cA + (size_t)(t + 2) * kstep; const char* b2 = last ? nB : cB + (size_t)(t + 2) * kstep;
;             const char* a3 = a2 + kstep; const char* b3 = b2 + kstep;
;     ...
; #pragma unroll
;         for (int a = 0; a < 2; ++a)
; #pragma unroll
;             for (int b = 0; b < 2; ++b)
; #pragma unroll
;                 for (int m = 0; m < 4; ++m)
; #pragma unroll
;                     for (int n = 0; n < 2; ++n) acc[a][b][m][n] = (f32x4){0.f, 0.f, 0.f, 0.f};
.LBB0_1721:
	s_ashr_i32 s21, s20, 31
	s_lshl_b64 s[22:23], s[20:21], 19
	s_add_u32 s22, s42, s22
	s_addc_u32 s23, s43, s23
	s_and_b64 s[26:27], s[0:1], exec
	s_cselect_b32 s21, s23, s29
	s_cselect_b32 s60, s22, s28
	s_ashr_i32 s19, s18, 31
	s_lshl_b64 s[26:27], s[18:19], 19
	s_add_u32 s26, s3, s26
	s_addc_u32 s27, s25, s27
	s_and_b64 s[34:35], s[0:1], exec
	s_cselect_b32 s19, s27, s31
	s_cselect_b32 s61, s26, s30
	s_add_u32 s28, s28, 0x40080
	s_addc_u32 s29, s29, 0
	s_add_u32 s62, s30, 0x100
	v_mov_b32_e32 v0, 0
	s_addc_u32 s63, s31, 0
	s_mov_b32 s64, -2
	v_mov_b32_e32 v1, v0
	v_mov_b32_e32 v2, v0
	v_mov_b32_e32 v3, v0
	v_mov_b32_e32 v4, v0
	v_mov_b32_e32 v5, v0
	v_mov_b32_e32 v6, v0
	v_mov_b32_e32 v7, v0
	v_mov_b32_e32 v16, v0
	v_mov_b32_e32 v17, v0
	v_mov_b32_e32 v18, v0
	v_mov_b32_e32 v19, v0
	v_mov_b32_e32 v20, v0
	v_mov_b32_e32 v21, v0
	v_mov_b32_e32 v22, v0
	v_mov_b32_e32 v23, v0
	v_mov_b32_e32 v32, v0
	v_mov_b32_e32 v33, v0
	s_waitcnt vmcnt(0)
	v_pk_mov_b32 v[8:9], v[0:1], v[0:1]
	v_pk_mov_b32 v[10:11], v[0:1], v[0:1]
	v_pk_mov_b32 v[12:13], v[0:1], v[0:1]
	v_pk_mov_b32 v[14:15], v[0:1], v[0:1]
	v_pk_mov_b32 v[24:25], v[0:1], v[0:1]
	v_pk_mov_b32 v[26:27], v[0:1], v[0:1]
	v_pk_mov_b32 v[28:29], v[0:1], v[0:1]
	v_pk_mov_b32 v[30:31], v[0:1], v[0:1]
	v_pk_mov_b32 v[34:35], v[0:1], v[0:1]
	v_pk_mov_b32 v[36:37], v[0:1], v[0:1]
	v_pk_mov_b32 v[38:39], v[0:1], v[0:1]
	v_pk_mov_b32 v[40:41], v[0:1], v[0:1]
	v_pk_mov_b32 v[42:43], v[0:1], v[0:1]
	v_pk_mov_b32 v[44:45], v[0:1], v[0:1]
	v_pk_mov_b32 v[46:47], v[0:1], v[0:1]
	v_pk_mov_b32 v[48:49], v[0:1], v[0:1]
	v_pk_mov_b32 v[50:51], v[0:1], v[0:1]
	v_pk_mov_b32 v[52:53], v[0:1], v[0:1]
	v_pk_mov_b32 v[54:55], v[0:1], v[0:1]
	v_pk_mov_b32 v[56:57], v[0:1], v[0:1]
	v_pk_mov_b32 v[58:59], v[0:1], v[0:1]
	v_pk_mov_b32 v[60:61], v[0:1], v[0:1]
	v_pk_mov_b32 v[62:63], v[0:1], v[0:1]
	v_pk_mov_b32 v[64:65], v[0:1], v[0:1]
	v_pk_mov_b32 v[66:67], v[0:1], v[0:1]
	v_pk_mov_b32 v[68:69], v[0:1], v[0:1]
	v_pk_mov_b32 v[70:71], v[0:1], v[0:1]
	v_pk_mov_b32 v[72:73], v[0:1], v[0:1]
	v_pk_mov_b32 v[74:75], v[0:1], v[0:1]
	v_pk_mov_b32 v[76:77], v[0:1], v[0:1]
	v_pk_mov_b32 v[78:79], v[0:1], v[0:1]
	v_pk_mov_b32 v[80:81], v[0:1], v[0:1]
	v_pk_mov_b32 v[82:83], v[0:1], v[0:1]
	v_pk_mov_b32 v[84:85], v[0:1], v[0:1]
	v_pk_mov_b32 v[86:87], v[0:1], v[0:1]
	v_pk_mov_b32 v[88:89], v[0:1], v[0:1]
	v_pk_mov_b32 v[90:91], v[0:1], v[0:1]
	v_pk_mov_b32 v[92:93], v[0:1], v[0:1]
	v_pk_mov_b32 v[94:95], v[0:1], v[0:1]
	v_pk_mov_b32 v[96:97], v[0:1], v[0:1]
	v_pk_mov_b32 v[98:99], v[0:1], v[0:1]
	v_pk_mov_b32 v[100:101], v[0:1], v[0:1]
	v_pk_mov_b32 v[102:103], v[0:1], v[0:1]
	v_pk_mov_b32 v[104:105], v[0:1], v[0:1]
	v_pk_mov_b32 v[106:107], v[0:1], v[0:1]
	v_pk_mov_b32 v[108:109], v[0:1], v[0:1]
	v_pk_mov_b32 v[110:111], v[0:1], v[0:1]
	v_pk_mov_b32 v[112:113], v[0:1], v[0:1]
	v_pk_mov_b32 v[114:115], v[0:1], v[0:1]
	v_pk_mov_b32 v[116:117], v[0:1], v[0:1]
	v_pk_mov_b32 v[118:119], v[0:1], v[0:1]
	v_pk_mov_b32 v[120:121], v[0:1], v[0:1]
	v_pk_mov_b32 v[122:123], v[0:1], v[0:1]
	v_pk_mov_b32 v[124:125], v[0:1], v[0:1]
	v_pk_mov_b32 v[126:127], v[0:1], v[0:1]

; template <class Epi>
; __device__ __forceinline__ void gemm_phase(LAS unsigned char* lds, const Gemm g, const StaticOrder& S, const Epi& E) {
;     ...
;             const char* a1 = cA + (size_t)(t + 1) * kstep;
;             const char* a2 = last ? nA : cA + (size_t)(t + 2) * kstep; const char* b2 = last ? nB : cB + (size_t)(t + 2) * kstep;
;     ...
; #pragma unroll
;         for (int a = 0; a < 2; ++a)
; #pragma unroll
;             for (int b = 0; b < 2; ++b)
; #pragma unroll
;                 for (int m = 0; m < 4; ++m)
; #pragma unroll
;                     for (int n = 0; n < 2; ++n) acc[a][b][m][n] = (f32x4){0.f, 0.f, 0.f, 0.f};
.LBB0_1813:
	s_add_u32 s83, s60, 0x100
	v_mov_b32_e32 v0, 0
	s_addc_u32 s84, s61, 0
	s_mov_b32 s85, -2
	v_mov_b32_e32 v1, v0
	v_mov_b32_e32 v2, v0
	v_mov_b32_e32 v3, v0
	v_mov_b32_e32 v4, v0
	v_mov_b32_e32 v5, v0
	v_mov_b32_e32 v6, v0
	v_mov_b32_e32 v7, v0
	v_mov_b32_e32 v16, v0
	v_mov_b32_e32 v17, v0
	v_mov_b32_e32 v18, v0
	v_mov_b32_e32 v19, v0
	v_mov_b32_e32 v20, v0
	v_mov_b32_e32 v21, v0
	v_mov_b32_e32 v22, v0
	v_mov_b32_e32 v23, v0
	v_mov_b32_e32 v32, v0
	v_mov_b32_e32 v33, v0
	s_waitcnt vmcnt(0)
	v_pk_mov_b32 v[8:9], v[0:1], v[0:1]
	v_pk_mov_b32 v[10:11], v[0:1], v[0:1]
	v_pk_mov_b32 v[12:13], v[0:1], v[0:1]
	v_pk_mov_b32 v[14:15], v[0:1], v[0:1]
	v_pk_mov_b32 v[24:25], v[0:1], v[0:1]
	v_pk_mov_b32 v[26:27], v[0:1], v[0:1]
	v_pk_mov_b32 v[28:29], v[0:1], v[0:1]
	v_pk_mov_b32 v[30:31], v[0:1], v[0:1]
	v_pk_mov_b32 v[34:35], v[0:1], v[0:1]
	v_pk_mov_b32 v[36:37], v[0:1], v[0:1]
	v_pk_mov_b32 v[38:39], v[0:1], v[0:1]
	v_pk_mov_b32 v[40:41], v[0:1], v[0:1]
	v_pk_mov_b32 v[42:43], v[0:1], v[0:1]
	v_pk_mov_b32 v[44:45], v[0:1], v[0:1]
	v_pk_mov_b32 v[46:47], v[0:1], v[0:1]
	v_pk_mov_b32 v[48:49], v[0:1], v[0:1]
	v_pk_mov_b32 v[50:51], v[0:1], v[0:1]
	v_pk_mov_b32 v[52:53], v[0:1], v[0:1]
	v_pk_mov_b32 v[54:55], v[0:1], v[0:1]
	v_pk_mov_b32 v[56:57], v[0:1], v[0:1]
	v_pk_mov_b32 v[58:59], v[0:1], v[0:1]
	v_pk_mov_b32 v[60:61], v[0:1], v[0:1]
	v_pk_mov_b32 v[62:63], v[0:1], v[0:1]
	v_pk_mov_b32 v[96:97], v[0:1], v[0:1]
	v_pk_mov_b32 v[98:99], v[0:1], v[0:1]
	v_pk_mov_b32 v[100:101], v[0:1], v[0:1]
	v_pk_mov_b32 v[102:103], v[0:1], v[0:1]
	v_pk_mov_b32 v[104:105], v[0:1], v[0:1]
	v_pk_mov_b32 v[106:107], v[0:1], v[0:1]
	v_pk_mov_b32 v[108:109], v[0:1], v[0:1]
	v_pk_mov_b32 v[110:111], v[0:1], v[0:1]
	v_pk_mov_b32 v[112:113], v[0:1], v[0:1]
	v_pk_mov_b32 v[114:115], v[0:1], v[0:1]
	v_pk_mov_b32 v[116:117], v[0:1], v[0:1]
	v_pk_mov_b32 v[118:119], v[0:1], v[0:1]
	v_pk_mov_b32 v[120:121], v[0:1], v[0:1]
	v_pk_mov_b32 v[122:123], v[0:1], v[0:1]
	v_pk_mov_b32 v[124:125], v[0:1], v[0:1]
	v_pk_mov_b32 v[126:127], v[0:1], v[0:1]
	v_pk_mov_b32 v[128:129], v[0:1], v[0:1]
	v_pk_mov_b32 v[130:131], v[0:1], v[0:1]
	v_pk_mov_b32 v[132:133], v[0:1], v[0:1]
	v_pk_mov_b32 v[134:135], v[0:1], v[0:1]
	v_pk_mov_b32 v[136:137], v[0:1], v[0:1]
	v_pk_mov_b32 v[138:139], v[0:1], v[0:1]
	v_pk_mov_b32 v[140:141], v[0:1], v[0:1]
	v_pk_mov_b32 v[142:143], v[0:1], v[0:1]
	v_pk_mov_b32 v[144:145], v[0:1], v[0:1]
	v_pk_mov_b32 v[146:147], v[0:1], v[0:1]
	v_pk_mov_b32 v[148:149], v[0:1], v[0:1]
	v_pk_mov_b32 v[150:151], v[0:1], v[0:1]
	v_pk_mov_b32 v[152:153], v[0:1], v[0:1]
	v_pk_mov_b32 v[154:155], v[0:1], v[0:1]
	v_pk_mov_b32 v[156:157], v[0:1], v[0:1]
	v_pk_mov_b32 v[158:159], v[0:1], v[0:1]
